# v41 with final-phase fast path remapped so each dwordx4 store writes 1 KiB contiguous
# speedup vs baseline: 1.0092x; 1.0092x over previous
.Lfin_fast:
	v_lshlrev_b32_e32 v172, 3, v36
	v_add_u32_e32 v172, 0x800, v172
	v_mov_b32_e32 v173, 0
	v_lshlrev_b32_e32 v174, 4, v36
	v_add_u32_e32 v174, 0x1000, v174
	v_mov_b32_e32 v175, 0
	v_sub_co_u32_e32 v50, vcc, v50, v172
	s_nop 1
	v_subb_co_u32_e32 v51, vcc, v51, v173, vcc
	v_sub_co_u32_e32 v52, vcc, v52, v174
	s_nop 1
	v_subb_co_u32_e32 v53, vcc, v53, v175, vcc
	v_cmp_gt_u32_e32 vcc, 32, v36
	s_load_dwordx2 s[4:5], s[30:31], 0xa0
	v_lshlrev_b32_e32 v176, 4, v36
	s_waitcnt lgkmcnt(0)
	global_load_dwordx4 v[0:3], v176, s[4:5] offset:0
	global_load_dwordx4 v[4:7], v176, s[4:5] offset:1024
	global_load_dwordx4 v[8:11], v176, s[4:5] offset:2048
	global_load_dwordx4 v[12:15], v176, s[4:5] offset:3072
	v_add_u32_e32 v177, 0x1000, v176
	global_load_dwordx4 v[16:19], v177, s[4:5] offset:0
	global_load_dwordx4 v[20:23], v177, s[4:5] offset:1024
	global_load_dwordx4 v[24:27], v177, s[4:5] offset:2048
	global_load_dwordx4 v[28:31], v177, s[4:5] offset:3072
	v_readlane_b32 s10, v209, 10
	v_readlane_b32 s11, v209, 11
	v_mov_b32_e32 v54, 0
	v_mov_b32_e32 v132, 0
	v_mov_b32_e32 v134, 0
	v_mov_b32_e32 v136, 0
	v_lshl_add_u64 v[146:147], v[48:49], 0, s[26:27]
	v_lshl_add_u64 v[148:149], v[146:147], 0, s[26:27]
	v_lshl_add_u64 v[150:151], v[148:149], 0, s[26:27]
	v_lshl_add_u64 v[140:141], v[50:51], 0, s[10:11]
	v_lshl_add_u64 v[142:143], v[140:141], 0, s[10:11]
	v_lshl_add_u64 v[144:145], v[142:143], 0, s[10:11]
	s_and_saveexec_b64 s[4:5], vcc
	global_load_dword v54, v[48:49], off
	global_load_dword v132, v[146:147], off
	global_load_dword v134, v[148:149], off
	global_load_dword v136, v[150:151], off
	s_or_b64 exec, exec, s[4:5]
	global_load_dwordx2 v[64:65], v[50:51], off
	global_load_dwordx2 v[66:67], v[50:51], off offset:512
	global_load_dwordx2 v[68:69], v[50:51], off offset:1024
	global_load_dwordx2 v[70:71], v[50:51], off offset:1536
	global_load_dwordx2 v[72:73], v[50:51], off offset:2048
	global_load_dwordx2 v[74:75], v[50:51], off offset:2560
	global_load_dwordx2 v[76:77], v[50:51], off offset:3072
	global_load_dwordx2 v[78:79], v[50:51], off offset:3584
	global_load_dwordx2 v[80:81], v[140:141], off
	global_load_dwordx2 v[82:83], v[140:141], off offset:512
	global_load_dwordx2 v[84:85], v[140:141], off offset:1024
	global_load_dwordx2 v[86:87], v[140:141], off offset:1536
	global_load_dwordx2 v[88:89], v[140:141], off offset:2048
	global_load_dwordx2 v[90:91], v[140:141], off offset:2560
	global_load_dwordx2 v[92:93], v[140:141], off offset:3072
	global_load_dwordx2 v[94:95], v[140:141], off offset:3584
	global_load_dwordx2 v[96:97], v[142:143], off
	global_load_dwordx2 v[98:99], v[142:143], off offset:512
	global_load_dwordx2 v[100:101], v[142:143], off offset:1024
	global_load_dwordx2 v[102:103], v[142:143], off offset:1536
	global_load_dwordx2 v[104:105], v[142:143], off offset:2048
	global_load_dwordx2 v[106:107], v[142:143], off offset:2560
	global_load_dwordx2 v[108:109], v[142:143], off offset:3072
	global_load_dwordx2 v[110:111], v[142:143], off offset:3584
	global_load_dwordx2 v[112:113], v[144:145], off
	global_load_dwordx2 v[114:115], v[144:145], off offset:512
	global_load_dwordx2 v[116:117], v[144:145], off offset:1024
	global_load_dwordx2 v[118:119], v[144:145], off offset:1536
	global_load_dwordx2 v[120:121], v[144:145], off offset:2048
	global_load_dwordx2 v[122:123], v[144:145], off offset:2560
	global_load_dwordx2 v[124:125], v[144:145], off offset:3072
	global_load_dwordx2 v[126:127], v[144:145], off offset:3584
	v_readlane_b32 s10, v209, 14
	v_readlane_b32 s11, v209, 15
	s_mov_b32 s8, 0x800000
	s_nop 1
	v_lshl_add_u64 v[152:153], v[52:53], 0, s[10:11]
	v_lshl_add_u64 v[154:155], v[152:153], 0, s[10:11]
	v_lshl_add_u64 v[156:157], v[154:155], 0, s[10:11]
	s_waitcnt vmcnt(32)
	ds_bpermute_b32 v160, v55, v54
	ds_bpermute_b32 v161, v55, v132
	ds_bpermute_b32 v162, v55, v134
	ds_bpermute_b32 v163, v55, v136
	s_waitcnt lgkmcnt(0)
	v_add_f32_e32 v54, v54, v160
	v_add_f32_e32 v132, v132, v161
	v_add_f32_e32 v134, v134, v162
	v_add_f32_e32 v136, v136, v163
	ds_bpermute_b32 v160, v56, v54
	ds_bpermute_b32 v161, v56, v132
	ds_bpermute_b32 v162, v56, v134
	ds_bpermute_b32 v163, v56, v136
	s_waitcnt lgkmcnt(0)
	v_add_f32_e32 v54, v54, v160
	v_add_f32_e32 v132, v132, v161
	v_add_f32_e32 v134, v134, v162
	v_add_f32_e32 v136, v136, v163
	ds_bpermute_b32 v160, v57, v54
	ds_bpermute_b32 v161, v57, v132
	ds_bpermute_b32 v162, v57, v134
	ds_bpermute_b32 v163, v57, v136
	s_waitcnt lgkmcnt(0)
	v_add_f32_e32 v54, v54, v160
	v_add_f32_e32 v132, v132, v161
	v_add_f32_e32 v134, v134, v162
	v_add_f32_e32 v136, v136, v163
	ds_bpermute_b32 v160, v58, v54
	ds_bpermute_b32 v161, v58, v132
	ds_bpermute_b32 v162, v58, v134
	ds_bpermute_b32 v163, v58, v136
	s_waitcnt lgkmcnt(0)
	v_add_f32_e32 v54, v54, v160
	v_add_f32_e32 v132, v132, v161
	v_add_f32_e32 v134, v134, v162
	v_add_f32_e32 v136, v136, v163
	ds_bpermute_b32 v160, v59, v54
	ds_bpermute_b32 v161, v59, v132
	ds_bpermute_b32 v162, v59, v134
	ds_bpermute_b32 v163, v59, v136
	s_waitcnt lgkmcnt(0)
	v_add_f32_e32 v54, v54, v160
	v_add_f32_e32 v132, v132, v161
	v_add_f32_e32 v134, v134, v162
	v_add_f32_e32 v136, v136, v163
	ds_bpermute_b32 v160, v60, v54
	ds_bpermute_b32 v161, v60, v132
	ds_bpermute_b32 v162, v60, v134
	ds_bpermute_b32 v163, v60, v136
	s_waitcnt lgkmcnt(0)
	v_add_f32_e32 v54, v54, v160
	v_add_f32_e32 v132, v132, v161
	v_add_f32_e32 v134, v134, v162
	v_add_f32_e32 v136, v136, v163
	v_fmamk_f32 v54, v54, 0x3a000000, v235
	v_fmamk_f32 v132, v132, 0x3a000000, v235
	v_fmamk_f32 v134, v134, 0x3a000000, v235
	v_fmamk_f32 v136, v136, 0x3a000000, v235
	v_cmp_gt_f32_e64 s[4:5], s8, v54
	v_mul_f32_e32 v160, 0x4b800000, v54
	v_cmp_gt_f32_e64 s[6:7], s8, v132
	v_mul_f32_e32 v161, 0x4b800000, v132
	v_cndmask_b32_e64 v54, v54, v160, s[4:5]
	v_cndmask_b32_e64 v132, v132, v161, s[6:7]
	v_rsq_f32_e32 v54, v54
	v_rsq_f32_e32 v132, v132
	v_mul_f32_e32 v160, 0x45800000, v54
	v_mul_f32_e32 v161, 0x45800000, v132
	v_cndmask_b32_e64 v54, v54, v160, s[4:5]
	v_cndmask_b32_e64 v132, v132, v161, s[6:7]
	v_cmp_gt_f32_e64 s[4:5], s8, v134
	v_mul_f32_e32 v160, 0x4b800000, v134
	v_cmp_gt_f32_e64 s[6:7], s8, v136
	v_mul_f32_e32 v161, 0x4b800000, v136
	v_cndmask_b32_e64 v134, v134, v160, s[4:5]
	v_cndmask_b32_e64 v136, v136, v161, s[6:7]
	v_rsq_f32_e32 v134, v134
	v_rsq_f32_e32 v136, v136
	v_mul_f32_e32 v160, 0x45800000, v134
	v_mul_f32_e32 v161, 0x45800000, v136
	v_cndmask_b32_e64 v134, v134, v160, s[4:5]
	v_cndmask_b32_e64 v136, v136, v161, s[6:7]
	s_waitcnt vmcnt(24)
	v_lshlrev_b32_e32 v164, 16, v64
	v_and_b32_e32 v165, 0xffff0000, v64
	v_lshlrev_b32_e32 v166, 16, v65
	v_and_b32_e32 v167, 0xffff0000, v65
	v_pk_mul_f32 v[164:165], v[54:55], v[164:165] op_sel_hi:[0,1]
	v_pk_mul_f32 v[166:167], v[54:55], v[166:167] op_sel_hi:[0,1]
	v_pk_mul_f32 v[164:165], v[0:1], v[164:165]
	v_pk_mul_f32 v[166:167], v[2:3], v[166:167]
	global_store_dwordx4 v[52:53], v[164:167], off
	v_lshlrev_b32_e32 v168, 16, v66
	v_and_b32_e32 v169, 0xffff0000, v66
	v_lshlrev_b32_e32 v170, 16, v67
	v_and_b32_e32 v171, 0xffff0000, v67
	v_pk_mul_f32 v[168:169], v[54:55], v[168:169] op_sel_hi:[0,1]
	v_pk_mul_f32 v[170:171], v[54:55], v[170:171] op_sel_hi:[0,1]
	v_pk_mul_f32 v[168:169], v[4:5], v[168:169]
	v_pk_mul_f32 v[170:171], v[6:7], v[170:171]
	global_store_dwordx4 v[52:53], v[168:171], off offset:1024
	v_lshlrev_b32_e32 v164, 16, v68
	v_and_b32_e32 v165, 0xffff0000, v68
	v_lshlrev_b32_e32 v166, 16, v69
	v_and_b32_e32 v167, 0xffff0000, v69
	v_pk_mul_f32 v[164:165], v[54:55], v[164:165] op_sel_hi:[0,1]
	v_pk_mul_f32 v[166:167], v[54:55], v[166:167] op_sel_hi:[0,1]
	v_pk_mul_f32 v[164:165], v[8:9], v[164:165]
	v_pk_mul_f32 v[166:167], v[10:11], v[166:167]
	global_store_dwordx4 v[52:53], v[164:167], off offset:2048
	v_lshlrev_b32_e32 v168, 16, v70
	v_and_b32_e32 v169, 0xffff0000, v70
	v_lshlrev_b32_e32 v170, 16, v71
	v_and_b32_e32 v171, 0xffff0000, v71
	v_pk_mul_f32 v[168:169], v[54:55], v[168:169] op_sel_hi:[0,1]
	v_pk_mul_f32 v[170:171], v[54:55], v[170:171] op_sel_hi:[0,1]
	v_pk_mul_f32 v[168:169], v[12:13], v[168:169]
	v_pk_mul_f32 v[170:171], v[14:15], v[170:171]
	global_store_dwordx4 v[52:53], v[168:171], off offset:3072
	v_mov_b32_e32 v180, 0x1000
	v_mov_b32_e32 v181, 0
	v_add_co_u32_e32 v178, vcc, v52, v180
	s_nop 1
	v_addc_co_u32_e32 v179, vcc, v53, v181, vcc
	v_lshlrev_b32_e32 v164, 16, v72
	v_and_b32_e32 v165, 0xffff0000, v72
	v_lshlrev_b32_e32 v166, 16, v73
	v_and_b32_e32 v167, 0xffff0000, v73
	v_pk_mul_f32 v[164:165], v[54:55], v[164:165] op_sel_hi:[0,1]
	v_pk_mul_f32 v[166:167], v[54:55], v[166:167] op_sel_hi:[0,1]
	v_pk_mul_f32 v[164:165], v[16:17], v[164:165]
	v_pk_mul_f32 v[166:167], v[18:19], v[166:167]
	global_store_dwordx4 v[178:179], v[164:167], off offset:0
	v_lshlrev_b32_e32 v168, 16, v74
	v_and_b32_e32 v169, 0xffff0000, v74
	v_lshlrev_b32_e32 v170, 16, v75
	v_and_b32_e32 v171, 0xffff0000, v75
	v_pk_mul_f32 v[168:169], v[54:55], v[168:169] op_sel_hi:[0,1]
	v_pk_mul_f32 v[170:171], v[54:55], v[170:171] op_sel_hi:[0,1]
	v_pk_mul_f32 v[168:169], v[20:21], v[168:169]
	v_pk_mul_f32 v[170:171], v[22:23], v[170:171]
	global_store_dwordx4 v[178:179], v[168:171], off offset:1024
	v_lshlrev_b32_e32 v164, 16, v76
	v_and_b32_e32 v165, 0xffff0000, v76
	v_lshlrev_b32_e32 v166, 16, v77
	v_and_b32_e32 v167, 0xffff0000, v77
	v_pk_mul_f32 v[164:165], v[54:55], v[164:165] op_sel_hi:[0,1]
	v_pk_mul_f32 v[166:167], v[54:55], v[166:167] op_sel_hi:[0,1]
	v_pk_mul_f32 v[164:165], v[24:25], v[164:165]
	v_pk_mul_f32 v[166:167], v[26:27], v[166:167]
	global_store_dwordx4 v[178:179], v[164:167], off offset:2048
	v_lshlrev_b32_e32 v168, 16, v78
	v_and_b32_e32 v169, 0xffff0000, v78
	v_lshlrev_b32_e32 v170, 16, v79
	v_and_b32_e32 v171, 0xffff0000, v79
	v_pk_mul_f32 v[168:169], v[54:55], v[168:169] op_sel_hi:[0,1]
	v_pk_mul_f32 v[170:171], v[54:55], v[170:171] op_sel_hi:[0,1]
	v_pk_mul_f32 v[168:169], v[28:29], v[168:169]
	v_pk_mul_f32 v[170:171], v[30:31], v[170:171]
	global_store_dwordx4 v[178:179], v[168:171], off offset:3072
	s_waitcnt vmcnt(24)
	v_lshlrev_b32_e32 v164, 16, v80
	v_and_b32_e32 v165, 0xffff0000, v80
	v_lshlrev_b32_e32 v166, 16, v81
	v_and_b32_e32 v167, 0xffff0000, v81
	v_pk_mul_f32 v[164:165], v[132:133], v[164:165] op_sel_hi:[0,1]
	v_pk_mul_f32 v[166:167], v[132:133], v[166:167] op_sel_hi:[0,1]
	v_pk_mul_f32 v[164:165], v[0:1], v[164:165]
	v_pk_mul_f32 v[166:167], v[2:3], v[166:167]
	global_store_dwordx4 v[152:153], v[164:167], off
	v_lshlrev_b32_e32 v168, 16, v82
	v_and_b32_e32 v169, 0xffff0000, v82
	v_lshlrev_b32_e32 v170, 16, v83
	v_and_b32_e32 v171, 0xffff0000, v83
	v_pk_mul_f32 v[168:169], v[132:133], v[168:169] op_sel_hi:[0,1]
	v_pk_mul_f32 v[170:171], v[132:133], v[170:171] op_sel_hi:[0,1]
	v_pk_mul_f32 v[168:169], v[4:5], v[168:169]
	v_pk_mul_f32 v[170:171], v[6:7], v[170:171]
	global_store_dwordx4 v[152:153], v[168:171], off offset:1024
	v_lshlrev_b32_e32 v164, 16, v84
	v_and_b32_e32 v165, 0xffff0000, v84
	v_lshlrev_b32_e32 v166, 16, v85
	v_and_b32_e32 v167, 0xffff0000, v85
	v_pk_mul_f32 v[164:165], v[132:133], v[164:165] op_sel_hi:[0,1]
	v_pk_mul_f32 v[166:167], v[132:133], v[166:167] op_sel_hi:[0,1]
	v_pk_mul_f32 v[164:165], v[8:9], v[164:165]
	v_pk_mul_f32 v[166:167], v[10:11], v[166:167]
	global_store_dwordx4 v[152:153], v[164:167], off offset:2048
	v_lshlrev_b32_e32 v168, 16, v86
	v_and_b32_e32 v169, 0xffff0000, v86
	v_lshlrev_b32_e32 v170, 16, v87
	v_and_b32_e32 v171, 0xffff0000, v87
	v_pk_mul_f32 v[168:169], v[132:133], v[168:169] op_sel_hi:[0,1]
	v_pk_mul_f32 v[170:171], v[132:133], v[170:171] op_sel_hi:[0,1]
	v_pk_mul_f32 v[168:169], v[12:13], v[168:169]
	v_pk_mul_f32 v[170:171], v[14:15], v[170:171]
	global_store_dwordx4 v[152:153], v[168:171], off offset:3072
	v_mov_b32_e32 v180, 0x1000
	v_mov_b32_e32 v181, 0
	v_add_co_u32_e32 v178, vcc, v152, v180
	s_nop 1
	v_addc_co_u32_e32 v179, vcc, v153, v181, vcc
	v_lshlrev_b32_e32 v164, 16, v88
	v_and_b32_e32 v165, 0xffff0000, v88
	v_lshlrev_b32_e32 v166, 16, v89
	v_and_b32_e32 v167, 0xffff0000, v89
	v_pk_mul_f32 v[164:165], v[132:133], v[164:165] op_sel_hi:[0,1]
	v_pk_mul_f32 v[166:167], v[132:133], v[166:167] op_sel_hi:[0,1]
	v_pk_mul_f32 v[164:165], v[16:17], v[164:165]
	v_pk_mul_f32 v[166:167], v[18:19], v[166:167]
	global_store_dwordx4 v[178:179], v[164:167], off offset:0
	v_lshlrev_b32_e32 v168, 16, v90
	v_and_b32_e32 v169, 0xffff0000, v90
	v_lshlrev_b32_e32 v170, 16, v91
	v_and_b32_e32 v171, 0xffff0000, v91
	v_pk_mul_f32 v[168:169], v[132:133], v[168:169] op_sel_hi:[0,1]
	v_pk_mul_f32 v[170:171], v[132:133], v[170:171] op_sel_hi:[0,1]
	v_pk_mul_f32 v[168:169], v[20:21], v[168:169]
	v_pk_mul_f32 v[170:171], v[22:23], v[170:171]
	global_store_dwordx4 v[178:179], v[168:171], off offset:1024
	v_lshlrev_b32_e32 v164, 16, v92
	v_and_b32_e32 v165, 0xffff0000, v92
	v_lshlrev_b32_e32 v166, 16, v93
	v_and_b32_e32 v167, 0xffff0000, v93
	v_pk_mul_f32 v[164:165], v[132:133], v[164:165] op_sel_hi:[0,1]
	v_pk_mul_f32 v[166:167], v[132:133], v[166:167] op_sel_hi:[0,1]
	v_pk_mul_f32 v[164:165], v[24:25], v[164:165]
	v_pk_mul_f32 v[166:167], v[26:27], v[166:167]
	global_store_dwordx4 v[178:179], v[164:167], off offset:2048
	v_lshlrev_b32_e32 v168, 16, v94
	v_and_b32_e32 v169, 0xffff0000, v94
	v_lshlrev_b32_e32 v170, 16, v95
	v_and_b32_e32 v171, 0xffff0000, v95
	v_pk_mul_f32 v[168:169], v[132:133], v[168:169] op_sel_hi:[0,1]
	v_pk_mul_f32 v[170:171], v[132:133], v[170:171] op_sel_hi:[0,1]
	v_pk_mul_f32 v[168:169], v[28:29], v[168:169]
	v_pk_mul_f32 v[170:171], v[30:31], v[170:171]
	global_store_dwordx4 v[178:179], v[168:171], off offset:3072
	s_waitcnt vmcnt(24)
	v_lshlrev_b32_e32 v164, 16, v96
	v_and_b32_e32 v165, 0xffff0000, v96
	v_lshlrev_b32_e32 v166, 16, v97
	v_and_b32_e32 v167, 0xffff0000, v97
	v_pk_mul_f32 v[164:165], v[134:135], v[164:165] op_sel_hi:[0,1]
	v_pk_mul_f32 v[166:167], v[134:135], v[166:167] op_sel_hi:[0,1]
	v_pk_mul_f32 v[164:165], v[0:1], v[164:165]
	v_pk_mul_f32 v[166:167], v[2:3], v[166:167]
	global_store_dwordx4 v[154:155], v[164:167], off
	v_lshlrev_b32_e32 v168, 16, v98
	v_and_b32_e32 v169, 0xffff0000, v98
	v_lshlrev_b32_e32 v170, 16, v99
	v_and_b32_e32 v171, 0xffff0000, v99
	v_pk_mul_f32 v[168:169], v[134:135], v[168:169] op_sel_hi:[0,1]
	v_pk_mul_f32 v[170:171], v[134:135], v[170:171] op_sel_hi:[0,1]
	v_pk_mul_f32 v[168:169], v[4:5], v[168:169]
	v_pk_mul_f32 v[170:171], v[6:7], v[170:171]
	global_store_dwordx4 v[154:155], v[168:171], off offset:1024
	v_lshlrev_b32_e32 v164, 16, v100
	v_and_b32_e32 v165, 0xffff0000, v100
	v_lshlrev_b32_e32 v166, 16, v101
	v_and_b32_e32 v167, 0xffff0000, v101
	v_pk_mul_f32 v[164:165], v[134:135], v[164:165] op_sel_hi:[0,1]
	v_pk_mul_f32 v[166:167], v[134:135], v[166:167] op_sel_hi:[0,1]
	v_pk_mul_f32 v[164:165], v[8:9], v[164:165]
	v_pk_mul_f32 v[166:167], v[10:11], v[166:167]
	global_store_dwordx4 v[154:155], v[164:167], off offset:2048
	v_lshlrev_b32_e32 v168, 16, v102
	v_and_b32_e32 v169, 0xffff0000, v102
	v_lshlrev_b32_e32 v170, 16, v103
	v_and_b32_e32 v171, 0xffff0000, v103
	v_pk_mul_f32 v[168:169], v[134:135], v[168:169] op_sel_hi:[0,1]
	v_pk_mul_f32 v[170:171], v[134:135], v[170:171] op_sel_hi:[0,1]
	v_pk_mul_f32 v[168:169], v[12:13], v[168:169]
	v_pk_mul_f32 v[170:171], v[14:15], v[170:171]
	global_store_dwordx4 v[154:155], v[168:171], off offset:3072
	v_mov_b32_e32 v180, 0x1000
	v_mov_b32_e32 v181, 0
	v_add_co_u32_e32 v178, vcc, v154, v180
	s_nop 1
	v_addc_co_u32_e32 v179, vcc, v155, v181, vcc
	v_lshlrev_b32_e32 v164, 16, v104
	v_and_b32_e32 v165, 0xffff0000, v104
	v_lshlrev_b32_e32 v166, 16, v105
	v_and_b32_e32 v167, 0xffff0000, v105
	v_pk_mul_f32 v[164:165], v[134:135], v[164:165] op_sel_hi:[0,1]
	v_pk_mul_f32 v[166:167], v[134:135], v[166:167] op_sel_hi:[0,1]
	v_pk_mul_f32 v[164:165], v[16:17], v[164:165]
	v_pk_mul_f32 v[166:167], v[18:19], v[166:167]
	global_store_dwordx4 v[178:179], v[164:167], off offset:0
	v_lshlrev_b32_e32 v168, 16, v106
	v_and_b32_e32 v169, 0xffff0000, v106
	v_lshlrev_b32_e32 v170, 16, v107
	v_and_b32_e32 v171, 0xffff0000, v107
	v_pk_mul_f32 v[168:169], v[134:135], v[168:169] op_sel_hi:[0,1]
	v_pk_mul_f32 v[170:171], v[134:135], v[170:171] op_sel_hi:[0,1]
	v_pk_mul_f32 v[168:169], v[20:21], v[168:169]
	v_pk_mul_f32 v[170:171], v[22:23], v[170:171]
	global_store_dwordx4 v[178:179], v[168:171], off offset:1024
	v_lshlrev_b32_e32 v164, 16, v108
	v_and_b32_e32 v165, 0xffff0000, v108
	v_lshlrev_b32_e32 v166, 16, v109
	v_and_b32_e32 v167, 0xffff0000, v109
	v_pk_mul_f32 v[164:165], v[134:135], v[164:165] op_sel_hi:[0,1]
	v_pk_mul_f32 v[166:167], v[134:135], v[166:167] op_sel_hi:[0,1]
	v_pk_mul_f32 v[164:165], v[24:25], v[164:165]
	v_pk_mul_f32 v[166:167], v[26:27], v[166:167]
	global_store_dwordx4 v[178:179], v[164:167], off offset:2048
	v_lshlrev_b32_e32 v168, 16, v110
	v_and_b32_e32 v169, 0xffff0000, v110
	v_lshlrev_b32_e32 v170, 16, v111
	v_and_b32_e32 v171, 0xffff0000, v111
	v_pk_mul_f32 v[168:169], v[134:135], v[168:169] op_sel_hi:[0,1]
	v_pk_mul_f32 v[170:171], v[134:135], v[170:171] op_sel_hi:[0,1]
	v_pk_mul_f32 v[168:169], v[28:29], v[168:169]
	v_pk_mul_f32 v[170:171], v[30:31], v[170:171]
	global_store_dwordx4 v[178:179], v[168:171], off offset:3072
	s_waitcnt vmcnt(24)
	v_lshlrev_b32_e32 v164, 16, v112
	v_and_b32_e32 v165, 0xffff0000, v112
	v_lshlrev_b32_e32 v166, 16, v113
	v_and_b32_e32 v167, 0xffff0000, v113
	v_pk_mul_f32 v[164:165], v[136:137], v[164:165] op_sel_hi:[0,1]
	v_pk_mul_f32 v[166:167], v[136:137], v[166:167] op_sel_hi:[0,1]
	v_pk_mul_f32 v[164:165], v[0:1], v[164:165]
	v_pk_mul_f32 v[166:167], v[2:3], v[166:167]
	global_store_dwordx4 v[156:157], v[164:167], off
	v_lshlrev_b32_e32 v168, 16, v114
	v_and_b32_e32 v169, 0xffff0000, v114
	v_lshlrev_b32_e32 v170, 16, v115
	v_and_b32_e32 v171, 0xffff0000, v115
	v_pk_mul_f32 v[168:169], v[136:137], v[168:169] op_sel_hi:[0,1]
	v_pk_mul_f32 v[170:171], v[136:137], v[170:171] op_sel_hi:[0,1]
	v_pk_mul_f32 v[168:169], v[4:5], v[168:169]
	v_pk_mul_f32 v[170:171], v[6:7], v[170:171]
	global_store_dwordx4 v[156:157], v[168:171], off offset:1024
	v_lshlrev_b32_e32 v164, 16, v116
	v_and_b32_e32 v165, 0xffff0000, v116
	v_lshlrev_b32_e32 v166, 16, v117
	v_and_b32_e32 v167, 0xffff0000, v117
	v_pk_mul_f32 v[164:165], v[136:137], v[164:165] op_sel_hi:[0,1]
	v_pk_mul_f32 v[166:167], v[136:137], v[166:167] op_sel_hi:[0,1]
	v_pk_mul_f32 v[164:165], v[8:9], v[164:165]
	v_pk_mul_f32 v[166:167], v[10:11], v[166:167]
	global_store_dwordx4 v[156:157], v[164:167], off offset:2048
	v_lshlrev_b32_e32 v168, 16, v118
	v_and_b32_e32 v169, 0xffff0000, v118
	v_lshlrev_b32_e32 v170, 16, v119
	v_and_b32_e32 v171, 0xffff0000, v119
	v_pk_mul_f32 v[168:169], v[136:137], v[168:169] op_sel_hi:[0,1]
	v_pk_mul_f32 v[170:171], v[136:137], v[170:171] op_sel_hi:[0,1]
	v_pk_mul_f32 v[168:169], v[12:13], v[168:169]
	v_pk_mul_f32 v[170:171], v[14:15], v[170:171]
	global_store_dwordx4 v[156:157], v[168:171], off offset:3072
	v_mov_b32_e32 v180, 0x1000
	v_mov_b32_e32 v181, 0
	v_add_co_u32_e32 v178, vcc, v156, v180
	s_nop 1
	v_addc_co_u32_e32 v179, vcc, v157, v181, vcc
	v_lshlrev_b32_e32 v164, 16, v120
	v_and_b32_e32 v165, 0xffff0000, v120
	v_lshlrev_b32_e32 v166, 16, v121
	v_and_b32_e32 v167, 0xffff0000, v121
	v_pk_mul_f32 v[164:165], v[136:137], v[164:165] op_sel_hi:[0,1]
	v_pk_mul_f32 v[166:167], v[136:137], v[166:167] op_sel_hi:[0,1]
	v_pk_mul_f32 v[164:165], v[16:17], v[164:165]
	v_pk_mul_f32 v[166:167], v[18:19], v[166:167]
	global_store_dwordx4 v[178:179], v[164:167], off offset:0
	v_lshlrev_b32_e32 v168, 16, v122
	v_and_b32_e32 v169, 0xffff0000, v122
	v_lshlrev_b32_e32 v170, 16, v123
	v_and_b32_e32 v171, 0xffff0000, v123
	v_pk_mul_f32 v[168:169], v[136:137], v[168:169] op_sel_hi:[0,1]
	v_pk_mul_f32 v[170:171], v[136:137], v[170:171] op_sel_hi:[0,1]
	v_pk_mul_f32 v[168:169], v[20:21], v[168:169]
	v_pk_mul_f32 v[170:171], v[22:23], v[170:171]
	global_store_dwordx4 v[178:179], v[168:171], off offset:1024
	v_lshlrev_b32_e32 v164, 16, v124
	v_and_b32_e32 v165, 0xffff0000, v124
	v_lshlrev_b32_e32 v166, 16, v125
	v_and_b32_e32 v167, 0xffff0000, v125
	v_pk_mul_f32 v[164:165], v[136:137], v[164:165] op_sel_hi:[0,1]
	v_pk_mul_f32 v[166:167], v[136:137], v[166:167] op_sel_hi:[0,1]
	v_pk_mul_f32 v[164:165], v[24:25], v[164:165]
	v_pk_mul_f32 v[166:167], v[26:27], v[166:167]
	global_store_dwordx4 v[178:179], v[164:167], off offset:2048
	v_lshlrev_b32_e32 v168, 16, v126
	v_and_b32_e32 v169, 0xffff0000, v126
	v_lshlrev_b32_e32 v170, 16, v127
	v_and_b32_e32 v171, 0xffff0000, v127
	v_pk_mul_f32 v[168:169], v[136:137], v[168:169] op_sel_hi:[0,1]
	v_pk_mul_f32 v[170:171], v[136:137], v[170:171] op_sel_hi:[0,1]
	v_pk_mul_f32 v[168:169], v[28:29], v[168:169]
	v_pk_mul_f32 v[170:171], v[30:31], v[170:171]
	global_store_dwordx4 v[178:179], v[168:171], off offset:3072
	s_branch .LBB0_27
